# v32 (prep_rows pipelined, 1.0953) + NA item epilogue z-load hoist; 2nd try of the NA hoist (v31 standalone validated, quick-time neutral, never pair-measured); 3rd variant since v30
# baseline (speedup 1.0000x reference)
; DI float bflo(unsigned u) { return __uint_as_float(u << 16); }
; DI float bfhi(unsigned u) { return __uint_as_float(u & 0xffff0000u); }
; DI float silu(float v) { return v * __builtin_amdgcn_rcpf(1.f + __expf(-v)); }
; DI u32x2 pack4(float a, float b, float c, float d) { u32x2 r; r.x = pack2(a, b); r.y = pack2(c, d); return r; }
; DI void na_phase(const Params& p, const u16* q, const u16* k, const u16* vt, const u16* z, u16* og, unsigned char* smem) {
;     ...
; #pragma unroll
;     for (int jj = 0; jj < 2; ++jj) {
;       float ls = lrun[jj];
;       ls += __shfl_xor(ls, 16);
;       ls += __shfl_xor(ls, 32);
;       const float inv = __builtin_amdgcn_rcpf(ls);
; #pragma unroll
;       for (int dt = 0; dt < 2; ++dt) {
;         const long off = ((long)b * 4096 + r * 64 + (jb + jj) * 16 + lq) * 1024 + h * 32 + dt * 16 + lg * 4;
;         const u32x2 zz = *(const u32x2*)(z + off);
;         *(u32x2*)(og + off) = pack4(o[jj][dt][0] * inv * silu(bflo(zz.x)), o[jj][dt][1] * inv * silu(bfhi(zz.x)),
;                                     o[jj][dt][2] * inv * silu(bflo(zz.y)), o[jj][dt][3] * inv * silu(bfhi(zz.y)));
;       }
;     }
.LBB0_231:
	v_or_b32_e32 v6, s97, v70
	v_or_b32_e32 v6, s82, v6
	v_mov_b32_e32 v7, s83
	v_mov_b32_e32 v5, s87
	v_or_b32_e32 v4, s86, v36
	v_lshlrev_b64 v[8:9], 10, v[6:7]
	v_lshl_add_u64 v[8:9], v[8:9], 0, v[4:5]
	v_lshlrev_b64 v[8:9], 1, v[8:9]
	v_lshl_add_u64 v[10:11], s[22:23], 0, v[8:9]
	global_load_dwordx2 v[10:11], v[10:11], off
	v_or_b32_e32 v206, 32, v8
	v_mov_b32_e32 v207, v9
	v_or_b32_e32 v208, s33, v70
	v_or_b32_e32 v208, s82, v208
	v_mov_b32_e32 v209, s83
	v_lshl_add_u64 v[206:207], s[22:23], 0, v[206:207]
	v_lshlrev_b64 v[208:209], 10, v[208:209]
	global_load_dwordx2 v[200:201], v[206:207], off
	v_lshl_add_u64 v[208:209], v[208:209], 0, v[4:5]
	v_lshlrev_b64 v[208:209], 1, v[208:209]
	v_lshl_add_u64 v[210:211], s[22:23], 0, v[208:209]
	v_or_b32_e32 v208, 32, v208
	global_load_dwordx2 v[202:203], v[210:211], off
	v_lshl_add_u64 v[208:209], s[22:23], 0, v[208:209]
	global_load_dwordx2 v[204:205], v[208:209], off
	v_cmp_lt_i32_e32 vcc, v67, v68
	s_add_i32 s95, s95, s42
	s_add_i32 s49, s49, s42
	v_cndmask_b32_e32 v6, v66, v67, vcc
	v_lshlrev_b32_e32 v27, 2, v6
	ds_bpermute_b32 v6, v27, v88
	v_cmp_lt_i32_e32 vcc, v69, v68
	s_cmpk_gt_i32 s95, 0x27ff
	s_waitcnt lgkmcnt(0)
	v_add_f32_e32 v6, v88, v6
	v_cndmask_b32_e32 v24, v66, v69, vcc
	v_lshlrev_b32_e32 v32, 2, v24
	ds_bpermute_b32 v26, v32, v6
	v_lshl_add_u64 v[24:25], s[14:15], 0, v[8:9]
	v_or_b32_e32 v8, 32, v8
	v_lshl_add_u64 v[8:9], s[22:23], 0, v[8:9]
	s_waitcnt lgkmcnt(0)
	v_add_f32_e32 v6, v6, v26
	v_rcp_f32_e32 v26, v6
	s_waitcnt vmcnt(3)
	v_lshlrev_b32_e32 v28, 16, v10
	v_and_b32_e32 v29, 0xffff0000, v10
	v_lshlrev_b32_e32 v10, 16, v11
	v_and_b32_e32 v11, 0xffff0000, v11
	v_mul_f32_e32 v6, 0xbfb8aa3b, v28
	v_mul_f32_e32 v30, 0xbfb8aa3b, v29
	v_mul_f32_e32 v31, 0xbfb8aa3b, v10
	v_mul_f32_e32 v71, 0xbfb8aa3b, v11
	v_exp_f32_e32 v6, v6
	v_exp_f32_e32 v30, v30
	v_exp_f32_e32 v31, v31
	v_exp_f32_e32 v71, v71
	v_add_f32_e32 v6, 1.0, v6
	v_add_f32_e32 v72, 1.0, v30
	v_add_f32_e32 v73, 1.0, v31
	v_add_f32_e32 v71, 1.0, v71
	v_rcp_f32_e32 v30, v6
	v_rcp_f32_e32 v31, v72
	v_rcp_f32_e32 v72, v73
	v_rcp_f32_e32 v73, v71
	v_pk_mul_f32 v[20:21], v[20:21], v[26:27] op_sel_hi:[1,0]
	v_pk_mul_f32 v[22:23], v[22:23], v[26:27] op_sel_hi:[1,0]
	v_pk_mul_f32 v[28:29], v[30:31], v[28:29]
	v_pk_mul_f32 v[10:11], v[72:73], v[10:11]
	v_pk_mul_f32 v[20:21], v[20:21], v[28:29]
	v_pk_mul_f32 v[10:11], v[22:23], v[10:11]
	v_cvt_pk_bf16_f32 v20, v20, v21
	v_cvt_pk_bf16_f32 v21, v10, v11
	global_store_dwordx2 v[24:25], v[20:21], off
	v_or_b32_e32 v6, s33, v70
	v_or_b32_e32 v6, s82, v6
	v_lshlrev_b64 v[6:7], 10, v[6:7]
	v_pk_mul_f32 v[16:17], v[16:17], v[26:27] op_sel_hi:[1,0]
	v_pk_mul_f32 v[18:19], v[18:19], v[26:27] op_sel_hi:[1,0]
	v_lshl_add_u64 v[4:5], v[6:7], 0, v[4:5]
	v_lshlrev_b64 v[4:5], 1, v[4:5]
	v_lshl_add_u64 v[6:7], s[22:23], 0, v[4:5]
	s_waitcnt vmcnt(3)
	v_lshlrev_b32_e32 v10, 16, v200
	v_and_b32_e32 v11, 0xffff0000, v200
	v_lshlrev_b32_e32 v8, 16, v201
	v_and_b32_e32 v9, 0xffff0000, v201
	v_mul_f32_e32 v20, 0xbfb8aa3b, v10
	v_mul_f32_e32 v21, 0xbfb8aa3b, v11
	v_mul_f32_e32 v22, 0xbfb8aa3b, v8
	v_mul_f32_e32 v23, 0xbfb8aa3b, v9
	v_exp_f32_e32 v20, v20
	v_exp_f32_e32 v21, v21
	v_exp_f32_e32 v22, v22
	v_exp_f32_e32 v23, v23
	v_add_f32_e32 v20, 1.0, v20
	v_add_f32_e32 v21, 1.0, v21
	v_add_f32_e32 v22, 1.0, v22
	v_add_f32_e32 v23, 1.0, v23
	v_rcp_f32_e32 v20, v20
	v_rcp_f32_e32 v21, v21
	v_rcp_f32_e32 v22, v22
	v_rcp_f32_e32 v23, v23
	v_pk_mul_f32 v[10:11], v[20:21], v[10:11]
	s_nop 0
	v_pk_mul_f32 v[10:11], v[16:17], v[10:11]
	v_pk_mul_f32 v[8:9], v[22:23], v[8:9]
	v_cvt_pk_bf16_f32 v10, v10, v11
	v_pk_mul_f32 v[8:9], v[18:19], v[8:9]
	s_nop 0
	v_cvt_pk_bf16_f32 v11, v8, v9
	global_store_dwordx2 v[24:25], v[10:11], off offset:32
	ds_bpermute_b32 v8, v27, v87
	s_waitcnt lgkmcnt(0)
	v_add_f32_e32 v10, v87, v8
	ds_bpermute_b32 v11, v32, v10
	v_lshl_add_u64 v[8:9], s[14:15], 0, v[4:5]
	v_or_b32_e32 v4, 32, v4
	v_lshl_add_u64 v[4:5], s[22:23], 0, v[4:5]
	s_waitcnt lgkmcnt(0)
	v_add_f32_e32 v10, v10, v11
	v_rcp_f32_e32 v10, v10
	s_waitcnt vmcnt(3)
	v_lshlrev_b32_e32 v16, 16, v202
	v_and_b32_e32 v17, 0xffff0000, v202
	v_lshlrev_b32_e32 v6, 16, v203
	v_and_b32_e32 v7, 0xffff0000, v203
	v_mul_f32_e32 v11, 0xbfb8aa3b, v16
	v_mul_f32_e32 v18, 0xbfb8aa3b, v17
	v_mul_f32_e32 v19, 0xbfb8aa3b, v6
	v_mul_f32_e32 v20, 0xbfb8aa3b, v7
	v_exp_f32_e32 v11, v11
	v_exp_f32_e32 v18, v18
	v_exp_f32_e32 v19, v19
	v_exp_f32_e32 v20, v20
	v_add_f32_e32 v11, 1.0, v11
	v_add_f32_e32 v21, 1.0, v18
	v_add_f32_e32 v22, 1.0, v19
	v_add_f32_e32 v23, 1.0, v20
	v_rcp_f32_e32 v18, v11
	v_rcp_f32_e32 v19, v21
	v_rcp_f32_e32 v20, v22
	v_rcp_f32_e32 v21, v23
	v_pk_mul_f32 v[12:13], v[12:13], v[10:11] op_sel_hi:[1,0]
	v_pk_mul_f32 v[14:15], v[14:15], v[10:11] op_sel_hi:[1,0]
	v_pk_mul_f32 v[16:17], v[18:19], v[16:17]
	v_pk_mul_f32 v[6:7], v[20:21], v[6:7]
	v_pk_mul_f32 v[12:13], v[12:13], v[16:17]
	v_pk_mul_f32 v[6:7], v[14:15], v[6:7]
	v_cvt_pk_bf16_f32 v12, v12, v13
	v_cvt_pk_bf16_f32 v13, v6, v7
	global_store_dwordx2 v[8:9], v[12:13], off
	s_waitcnt vmcnt(3)
	v_lshlrev_b32_e32 v6, 16, v204
	v_and_b32_e32 v7, 0xffff0000, v204
	v_lshlrev_b32_e32 v4, 16, v205
	v_and_b32_e32 v5, 0xffff0000, v205
	v_mul_f32_e32 v11, 0xbfb8aa3b, v6
	v_mul_f32_e32 v12, 0xbfb8aa3b, v7
	v_mul_f32_e32 v13, 0xbfb8aa3b, v4
	v_mul_f32_e32 v14, 0xbfb8aa3b, v5
	v_exp_f32_e32 v11, v11
	v_exp_f32_e32 v12, v12
	v_exp_f32_e32 v13, v13
	v_exp_f32_e32 v14, v14
	v_add_f32_e32 v11, 1.0, v11
	v_add_f32_e32 v15, 1.0, v12
	v_add_f32_e32 v16, 1.0, v13
	v_add_f32_e32 v17, 1.0, v14
	v_rcp_f32_e32 v12, v11
	v_rcp_f32_e32 v13, v15
	v_rcp_f32_e32 v14, v16
	v_rcp_f32_e32 v15, v17
	v_pk_mul_f32 v[0:1], v[0:1], v[10:11] op_sel_hi:[1,0]
	v_pk_mul_f32 v[2:3], v[2:3], v[10:11] op_sel_hi:[1,0]
	v_pk_mul_f32 v[6:7], v[12:13], v[6:7]
	v_pk_mul_f32 v[4:5], v[14:15], v[4:5]
	v_pk_mul_f32 v[0:1], v[0:1], v[6:7]
	v_pk_mul_f32 v[2:3], v[2:3], v[4:5]
	v_cvt_pk_bf16_f32 v0, v0, v1
	v_cvt_pk_bf16_f32 v1, v2, v3
	global_store_dwordx2 v[8:9], v[0:1], off offset:32
	s_cbranch_scc1 .LBB0_280
